# prep phase: the three remaining parameter loads ahead of the second load batch issued together with counted waits
# baseline (speedup 1.0000x reference)
.LBB0_379:
	s_or_b64 exec, exec, s[2:3]
	global_load_dword v248, v[30:31], off
	global_load_dword v249, v[30:31], off offset:256
	global_load_dword v250, v[30:31], off offset:512
	v_readlane_b32 s4, v252, 48
	v_lshlrev_b64 v[144:145], 11, v[106:107]
	v_readlane_b32 s6, v252, 50
	v_readlane_b32 s7, v252, 51
	s_waitcnt vmcnt(25)
	v_add_f32_e32 v93, v93, v207
	v_fma_f32 v93, v93, 0.5, -v185
	v_lshl_add_u64 v[142:143], s[6:7], 0, v[144:145]
	v_mov_b32_e32 v141, v1
	v_lshl_add_u64 v[146:147], v[142:143], 0, v[140:141]
	s_mov_b64 s[2:3], 0xc00
	v_mov_b32_e32 v230, 0
	v_mov_b32_e32 v231, 0
	v_readlane_b32 s5, v252, 49
	v_readlane_b32 s8, v252, 52
	v_readlane_b32 s9, v252, 53
	v_readlane_b32 s10, v252, 54
	v_readlane_b32 s11, v252, 55
	v_readlane_b32 s12, v252, 56
	v_readlane_b32 s13, v252, 57
	v_readlane_b32 s14, v252, 58
	v_readlane_b32 s15, v252, 59
	v_readlane_b32 s16, v252, 60
	v_readlane_b32 s17, v252, 61
	v_readlane_b32 s18, v252, 62
	v_readlane_b32 s19, v252, 63
	s_waitcnt vmcnt(2)
	v_mov_b32_e32 v0, v248
	v_fmac_f32_e32 v185, v93, v0
	global_store_dword v[146:147], v185, off
	v_add_f32_e32 v93, v204, v210
	v_fma_f32 v93, v93, 0.5, -v205
	s_waitcnt vmcnt(2)
	v_mov_b32_e32 v0, v249
	v_fmac_f32_e32 v205, v93, v0
	global_store_dword v[146:147], v205, off offset:256
	v_add_f32_e32 v93, v209, v212
	v_fma_f32 v93, v93, 0.5, -v211
	s_waitcnt vmcnt(2)
	v_mov_b32_e32 v0, v250
	v_fmac_f32_e32 v211, v93, v0
	v_lshlrev_b32_e32 v0, 2, v32
	global_store_dword v[146:147], v211, off offset:512
	v_lshl_add_u64 v[148:149], v[138:139], 0, v[0:1]
	global_load_dword v224, v[148:149], off offset:3072
	v_lshl_add_u64 v[140:141], v[148:149], 0, s[2:3]
	s_and_saveexec_b64 s[2:3], s[44:45]
	s_cbranch_execz .LBB0_381
	v_add_co_u32_e32 v148, vcc, 0xffffe000, v140
	s_nop 1
	v_addc_co_u32_e32 v149, vcc, -1, v141, vcc
	global_load_dword v231, v[148:149], off offset:-3072
